# P6 CU split with 120 prompt-attention WGs / 136 sample-attention WGs
# baseline (speedup 1.0000x reference)
; __device__ __forceinline__ void attn_mfma_phase(LAS unsigned char* lds, const bf16* QKVb, bf16* OPART, float2* ML, int tid, int wave, int lane) {
;     ...
;     if ((int)blockIdx.x < 1536) issue(blockIdx.x);
;     for (int item = blockIdx.x; item < 1536; item += gridDim.x) {
;         int h, b, r, bk; decode(item, h, b, r, bk);
;         const int d = 1 << (2 * b), L0 = bk * 256;
.LBB0_986:
	s_cmpk_ge_i32 s86, 120
	s_cselect_b32 s86, 0x600, s86
	s_cmpk_lt_i32 s86, 0x600
	s_cselect_b64 s[0:1], -1, 0
	s_cmpk_gt_i32 s86, 0x5ff
	s_cbranch_scc1 .LBB0_1008
	s_mul_hi_i32 s2, s86, 0x2aaaaaab
	s_lshr_b32 s3, s2, 31
	s_ashr_i32 s6, s2, 5
	s_add_i32 s6, s6, s3
	s_mul_i32 s2, s6, 0xc0
	s_sub_i32 s7, s86, s2
	s_cmp_lt_i32 s7, 64
	s_mov_b32 s2, 0
	s_cbranch_scc1 .LBB0_990
	s_cmpk_gt_u32 s7, 0x7f
	s_cbranch_scc0 .LBB0_991
	s_add_i32 s2, s7, 0xffffff80
	s_lshr_b32 s2, s2, 2
	s_and_b32 s8, s7, 3
	s_mov_b32 s3, 4
	s_cbranch_execz .LBB0_992
	s_branch .LBB0_993

; #define LAS __attribute__((address_space(3)))
; __device__ __forceinline__ void attn_mfma_phase(LAS unsigned char* lds, const bf16* QKVb, bf16* OPART, float2* ML, int tid, int wave, int lane) {
;     ...
;     for (int item = blockIdx.x; item < 1536; item += gridDim.x) {
;         int h, b, r, bk; decode(item, h, b, r, bk);
;         const int d = 1 << (2 * b), L0 = bk * 256;
; #pragma unroll
;         for (int c = 0; c < 6; ++c) { const int e = tid + NTHR * c, j = e >> 3, ch = e & 7;
;             *(LAS v4u*)(kimg + j * RSK + 16 * ch) = pk[c]; *(LAS v4u*)(vimg + j * RSV + 16 * ch) = pv[c]; }
;         const int l0 = L0 + 32 * wave;
;         const int tok_q = (l0 + i) * d + r;
;         const bf16* qp = QKVb + (size_t)tok_q * INW + C_QA + h * 64 + 8 * hh;
;         bf16x8 qf[4];
; #pragma unroll
;         for (int ks = 0; ks < 4; ++ks) qf[ks] = *(const bf16x8*)(qp + 16 * ks);
;         __syncthreads();
;         if (item + (int)gridDim.x < 1536) issue(item + gridDim.x);
.LBB0_1018:
	s_lshl_b32 s87, s84, 8
	s_add_i32 s87, s87, s2
	s_lshl_b32 s70, s1, 1
	v_or_b32_e32 v2, s87, v133
	v_lshlrev_b32_e32 v2, s70, v2
	v_readlane_b32 s70, v254, 55
	v_readlane_b32 s71, v254, 56
	v_add_u32_e32 v148, s33, v2
	s_lshl_b32 s94, s0, 6
	v_mov_b64_e32 v[2:3], s[70:71]
	v_mad_i64_i32 v[2:3], s[70:71], v148, s3, v[2:3]
	s_ashr_i32 s95, s94, 31
	v_lshl_add_u64 v[2:3], s[94:95], 1, v[2:3]
	v_lshl_add_u64 v[2:3], v[2:3], 0, v[142:143]
	global_load_dwordx4 v[114:117], v[2:3], off
	global_load_dwordx4 v[118:121], v[2:3], off offset:32
	global_load_dwordx4 v[122:125], v[2:3], off offset:64
	global_load_dwordx4 v[126:129], v[2:3], off offset:96
	s_movk_i32 s33, 120
	s_add_i32 s86, s86, s33
	s_cmpk_gt_i32 s86, 0x5ff
	s_cselect_b64 s[72:73], -1, 0
	v_add_u32_e32 v2, v135, v155
	s_and_b64 vcc, exec, s[72:73]
	s_waitcnt vmcnt(5)
	ds_write_b128 v159, v[70:73]
	s_waitcnt vmcnt(4)
	ds_write_b128 v2, v[66:69] offset:55296
	ds_write_b128 v160, v[78:81]
	ds_write_b128 v161, v[74:77] offset:55296
	ds_write_b128 v159, v[86:89] offset:18432
	ds_write_b128 v168, v[82:85] offset:55296
	ds_write_b128 v169, v[94:97]
	ds_write_b128 v170, v[90:93] offset:55296
	ds_write_b128 v159, v[102:105] offset:36864
	ds_write_b128 v171, v[98:101] offset:55296
	ds_write_b128 v172, v[110:113]
	ds_write_b128 v173, v[106:109] offset:55296
	s_waitcnt lgkmcnt(0)
	s_barrier
	s_cbranch_vccnz .LBB0_1039
	s_mul_hi_i32 s33, s86, 0x2aaaaaab
	s_lshr_b32 s70, s33, 31
	s_ashr_i32 s96, s33, 5
	s_add_i32 s96, s96, s70
	s_mul_i32 s33, s96, 0xc0
	s_sub_i32 s70, s86, s33
	s_cmp_lt_i32 s70, 64
	s_mov_b32 s84, 0
	s_cbranch_scc1 .LBB0_1025
	s_cmpk_gt_u32 s70, 0x7f
	s_mov_b64 s[92:93], -1
	s_cbranch_scc0 .LBB0_1022
	s_add_i32 s33, s70, 0xffffff80
	s_lshr_b32 s84, s33, 2
	s_and_b32 s33, s70, 3
	s_mov_b64 s[92:93], 0

; __global__ void __launch_bounds__(NTHR, 2) mk_fwd(Args a) {
;     ...
;     {
;         const int NI = NGW - DBATCH * SA_CH;
;         if (NI > 0 && NI <= G) {
;             const int bx = (int)blockIdx.x;
;             if (bx < NI && wave == NWAVES - 1) { ret_upd_wait_wave(ctlw + CW_UPD, ctlw + CW_TMO, lane); ret_scan_phase(P.UPD, P.SPT, P.out, bx * 64 + lane, NI * 64); }
;             else attn_sample_phase(P.QKVb, P.ck, P.cv, P.out, P.SPART, P.SML, bx < NI ? bx * (NWAVES - 1) + wave : NI * (NWAVES - 1) + (bx - NI) * NWAVES + wave, 1 << 20, lane);
.LBB0_1067:
	s_add_u32 s14, s90, 0x2d000000
	s_addc_u32 s15, s91, 0
	s_add_u32 s16, s90, 0x2e000000
	s_addc_u32 s17, s91, 0
	s_add_i32 s18, s69, 0xfffff880
	s_max_i32 s0, s18, 0xf1
	s_cmp_gt_i32 s0, s87
	s_mov_b64 s[0:1], -1
	s_cbranch_scc1 .LBB0_1177
	s_cmpk_lt_i32 s86, 120
	s_cbranch_scc1 .LBB0_1176
	v_readlane_b32 s4, v254, 34
	s_nop 3
	s_sub_i32 s0, s86, 120
	s_lshl_b32 s0, s0, 3
	s_add_i32 s0, s0, s4
	s_mov_b32 s99, s0
	s_cmpk_lt_i32 s0, 0x3c0
	s_mov_b64 s[4:5], -1
	s_cbranch_scc0 .LBB0_1151

; __device__ __forceinline__ void attn_sample_phase(const bf16* QKVb, const float* ck, const float* cv, const float* out, bf16* SPART, float2* SML, int gw, int NGW, int lane) {
;     const int l16 = lane & 15, hq = lane >> 4;
;     for (int item = gw; item < DBATCH * SA_CH; item += NGW) {
.LBB0_1075:
	s_or_b64 exec, exec, s[6:7]
	s_addk_i32 s0, 0x440
	s_cmpk_gt_i32 s0, 0x77f
	s_nop 0
	s_cbranch_scc1 .LBB0_1150

; __device__ __forceinline__ void ret_scan_phase(const float* __restrict__ UPDT, bf16* __restrict__ SPT, float* __restrict__ out, int first, int stride) {
;     if (first >= 0)
;     for (int e = first; e < 32768; e += stride) {
;         const int h = e >> 13, dv = (e >> 6) & 127, dk = e & 63;
;         const float G = expf(128.f * log_g(h));
;         float S = 0.f;
;         {
;             auto ldb = [&](int n0, float (&u)[16]) {
; #pragma unroll
;                 for (int k = 0; k < 16; ++k) u[k] = UPDT[(size_t)(n0 + k) * 32768 + e]; };
.LBB0_1162:
	s_waitcnt vmcnt(0) lgkmcnt(0)
	buffer_inv sc1
	s_waitcnt vmcnt(0)
	s_sub_i32 s1, s99, 0x3c0
	s_lshl_b32 s1, s1, 6
	s_cmpk_gt_u32 s1, 0x7fff
	s_movk_i32 s2, 0x7fff
	s_cbranch_scc1 .Lscan_done
	s_lshl_b32 s0, s18, 6
	v_add_u32_e32 v6, s1, v162
	v_or_b32_e32 v2, s1, v162
	v_ashrrev_i32_e32 v7, 31, v6
	s_ashr_i32 s1, s0, 31
	v_lshlrev_b64 v[4:5], 1, v[6:7]
	s_lshl_b64 s[4:5], s[0:1], 1
	v_lshlrev_b64 v[6:7], 2, v[6:7]
	s_lshl_b64 s[8:9], s[0:1], 2
	s_mov_b64 s[6:7], 0
	s_mov_b32 s11, 0
	s_mov_b32 s1, 0x22870000
	s_mov_b32 s3, 0x22880000
	s_mov_b32 s26, 0x22890000
	s_mov_b32 s27, 0x228a0000
	s_mov_b32 s28, 0x228b0000
	s_mov_b32 s29, 0x228c0000
	s_mov_b32 s30, 0x228d0000
	s_mov_b64 s[12:13], 0x200000
	s_mov_b64 s[18:19], 0x400000
	v_mov_b32_e32 v9, 0
	v_mov_b32_e32 v18, 0x3f1b1eb1
	v_mov_b32_e32 v19, 0x3ebb9db9
